# dilated unit: the Q fragment loads are no longer waited before the first K/V stage DMAs (the in-order vmcnt(2) tile wait covers them)
# baseline (speedup 1.0000x reference)
.LBB0_1392:
	s_ashr_i32 s4, s37, 7
	s_mul_hi_i32 s5, s4, 0x55555556
	s_lshr_b32 s12, s5, 31
	s_add_i32 s5, s5, s12
	s_mul_i32 s5, s5, 3
	s_ashr_i32 s0, s37, 5
	s_and_b32 s1, s37, 31
	s_sub_i32 s4, s4, s5
	s_cmp_eq_u32 s4, 0
	s_cselect_b64 s[14:15], -1, 0
	s_cmp_eq_u32 s4, 1
	s_cselect_b64 s[16:17], -1, 0
	s_and_b64 s[4:5], s[16:17], exec
	s_cselect_b32 s12, 2, 4
	s_and_b64 s[4:5], s[14:15], exec
	s_cselect_b32 s4, 0, s12
	s_lshr_b32 s5, 32, s4
	s_sub_i32 s12, 5, s4
	s_add_i32 s5, s5, -1
	v_readfirstlane_b32 s42, v0
	s_lshr_b32 s12, s1, s12
	s_and_b32 s20, s5, s1
	s_ashr_i32 s46, s42, 6
	s_ashr_i32 s1, s0, 31
	s_lshl_b64 s[18:19], s[0:1], 13
	s_lshl_b32 s0, s20, 8
	s_lshl_b32 s38, s46, 5
	s_add_i32 s38, s38, s0
	v_or_b32_e32 v2, s38, v1
	v_ashrrev_i32_e32 v3, 31, v2
	s_or_b32 s18, s18, s12
	v_lshlrev_b64 v[2:3], s4, v[2:3]
	v_lshl_add_u64 v[108:109], v[2:3], 0, s[18:19]
	v_lshlrev_b64 v[2:3], 7, v[108:109]
	v_lshl_add_u64 v[2:3], v[102:103], 0, v[2:3]
	global_load_dwordx4 v[66:69], v[2:3], off offset:96
	global_load_dwordx4 v[70:73], v[2:3], off offset:64
	global_load_dwordx4 v[74:77], v[2:3], off offset:32
	global_load_dwordx4 v[78:81], v[2:3], off
	s_lshl_b32 s0, s46, 8
	s_add_i32 s39, s0, 0
	s_add_i32 s39, s39, 0x18840
	s_lshl_b64 s[0:1], s[18:19], 7
	s_add_u32 s4, s24, s0
	s_addc_u32 s5, s25, s1
	s_add_u32 s0, s22, s0
	s_addc_u32 s1, s23, s1
	s_lshl_b32 s45, s20, 2
	s_add_i32 s43, s45, -2
	s_cmp_lg_u32 s20, 0
	s_cselect_b32 s12, s43, 0
	s_or_b32 s20, s45, 3
	s_sub_i32 s44, s20, s12
	s_lshl_b64 s[28:29], s[12:13], 6
	s_and_b64 s[40:41], s[16:17], exec
	s_cselect_b32 s20, 8, 10
	s_and_b64 s[40:41], s[14:15], exec
	v_mov_b32_e32 v3, s29
	v_mov_b32_e32 v5, s29
	s_cselect_b32 s40, 6, s20
	s_lshl_b32 s48, s46, 3
	s_lshl_b32 s29, s46, 10
	s_lshl_b32 s46, s46, 4
	s_and_b32 s46, s46, 48
	s_mov_b32 s21, s13
	v_or_b32_e32 v2, s28, v138
	s_or_b32 s20, s12, 1
	s_or_b32 s28, s28, s46
	s_ashr_i32 s49, s48, 31
	s_and_b32 s50, s48, 0xffffffe0
	s_lshl_b64 s[52:53], s[20:21], 6
	v_or_b32_e32 v4, s28, v104
	v_lshlrev_b64 v[2:3], s40, v[2:3]
	s_lshl_b64 s[20:21], s[48:49], 1
	s_ashr_i32 s51, s50, 31
	s_or_b32 s49, s52, s46
	v_lshlrev_b64 v[4:5], s40, v[4:5]
	s_add_i32 s41, s29, 0
	v_lshl_add_u64 v[2:3], v[2:3], 1, s[4:5]
	v_mov_b32_e32 v7, s53
	v_or_b32_e32 v6, s52, v138
	v_mov_b32_e32 v9, s53
	s_lshl_b64 s[28:29], s[50:51], 1
	v_or_b32_e32 v8, s49, v104
	v_lshl_add_u64 v[4:5], v[4:5], 1, s[0:1]
	v_lshl_add_u64 v[2:3], v[2:3], 0, s[20:21]
	v_lshlrev_b64 v[6:7], s40, v[6:7]
	v_lshlrev_b64 v[8:9], s40, v[8:9]
	v_lshl_add_u64 v[4:5], v[4:5], 0, s[28:29]
	s_add_i32 s47, s41, 0x8000
	v_lshl_add_u64 v[6:7], v[6:7], 1, s[4:5]
	v_lshl_add_u64 v[8:9], v[8:9], 1, s[0:1]
	v_lshl_add_u64 v[4:5], v[4:5], 0, v[100:101]
	s_add_i32 s48, s41, 0x2000
	v_lshl_add_u64 v[6:7], v[6:7], 0, s[20:21]
	v_lshl_add_u64 v[8:9], v[8:9], 0, s[28:29]
	v_lshl_add_u64 v[8:9], v[8:9], 0, v[100:101]
	v_lshl_add_u32 v132, v1, 2, s39
	s_mov_b32 s49, m0
	s_mov_b32 m0, s41
	s_nop 0
	global_load_lds_dwordx4 v[2:3], off
	s_mov_b32 m0, s49
	s_nop 0
	s_mov_b32 s49, m0
	s_mov_b32 m0, s47
	s_nop 0
	global_load_lds_dwordx4 v[4:5], off
	s_mov_b32 m0, s49
	s_mov_b32 s47, m0
	s_mov_b32 m0, s48
	s_nop 0
	global_load_lds_dwordx4 v[6:7], off
	s_mov_b32 m0, s47
	s_add_i32 s47, s41, 0xa000
	s_mov_b32 s48, m0
	s_mov_b32 m0, s47
	s_nop 0
	global_load_lds_dwordx4 v[8:9], off
	s_mov_b32 m0, s48
	s_waitcnt vmcnt(2) lgkmcnt(0)
	s_barrier
	s_cmp_lt_i32 s44, 0
	s_cbranch_scc1 .LBB0_1408
	s_ashr_i32 s47, s42, 7
	s_add_i32 s42, s47, s43
	s_add_i32 s43, s47, s45
	s_add_i32 s44, s44, -2
	s_add_u32 s20, s4, s20
	s_addc_u32 s21, s5, s21
	s_add_u32 s0, s0, s28
	s_addc_u32 s1, s1, s29
	v_lshl_add_u64 v[110:111], s[0:1], 0, v[100:101]
	s_sub_i32 s0, s12, s45
	s_add_i32 s0, s0, -4
	v_add_u32_e32 v2, s38, v129
	s_lshl_b32 s1, s12, 6
	s_not_b32 s45, s12
	v_mov_b32_e32 v134, 0
	v_or_b32_e32 v112, s46, v104
	v_subrev_u32_e32 v135, s1, v2
	s_add_i32 s45, s45, s43
	v_mov_b32_e32 v133, 0xff61b1e6
	s_mov_b32 s46, 0
	v_mov_b32_e32 v136, s0
	s_mov_b32 s47, 0
	v_mov_b32_e32 v2, 0
	v_mov_b32_e32 v3, v134
	v_mov_b32_e32 v4, v134
	v_mov_b32_e32 v5, v134
	v_mov_b32_e32 v6, v134
	v_mov_b32_e32 v7, v134
	v_mov_b32_e32 v8, v134
	v_mov_b32_e32 v9, v134
	v_mov_b32_e32 v10, v134
	v_mov_b32_e32 v11, v134
	v_mov_b32_e32 v12, v134
	v_mov_b32_e32 v13, v134
	v_mov_b32_e32 v14, v134
	v_mov_b32_e32 v15, v134
	v_mov_b32_e32 v16, v134
	v_mov_b32_e32 v17, v134
	v_mov_b32_e32 v18, 0
	v_mov_b32_e32 v19, v134
	v_mov_b32_e32 v20, v134
	v_mov_b32_e32 v21, v134
	v_mov_b32_e32 v22, v134
	v_mov_b32_e32 v23, v134
	v_mov_b32_e32 v24, v134
	v_mov_b32_e32 v25, v134
	v_mov_b32_e32 v26, v134
	v_mov_b32_e32 v27, v134
	v_mov_b32_e32 v28, v134
	v_mov_b32_e32 v29, v134
	v_mov_b32_e32 v30, v134
	v_mov_b32_e32 v31, v134
	v_mov_b32_e32 v32, v134
	v_mov_b32_e32 v33, v134
	s_branch .LBB0_1395
